# attention unit epilogue: gain vector read from a per-wave LDS copy (staged once per phase) instead of 16 global loads + vmcnt(0) drains per unit
# speedup vs baseline: 1.0171x; 1.0046x over previous
; __device__ __forceinline__ void ph_attn(const TI ti, CArgs& a, int l, bool ctx_out, unsigned char* ldsg) {
;     const int lane = ti.tid & 63;
;     const float gqm = fabsf(a.in[12][l * 64 + lane]), gkm = fabsf(a.in[13][l * 64 + lane]);
;     float mq = gqm, mk = gkm;
; #pragma unroll
;     for (int o = 1; o < 64; o <<= 1) { mq = fmaxf(mq, __shfl_xor(mq, o)); mk = fmaxf(mk, __shfl_xor(mk, o)); }
;     const float mfix = 8.f * mq * mk * 1.4426950408889634f * 1.03f;
;     const float* lp = a.in[14] + l * 256;
;     const float s1 = wave_sum(lp[lane] * lp[64 + lane]), s2 = wave_sum(lp[128 + lane] * lp[192 + lane]);
;     const float lam_init = 0.8f - 0.6f * expf(-0.3f * (float)l);
;     const float lam = expf(s1) - expf(s2) + lam_init;
;     const float* subg = a.in[15] + l * 128;
;     const int nun = 1024 + (ctx_out ? 128 : 0);
;     for (int u = ti.bid; u < nun; u += ti.nblk) {
.LBB0_329:
	s_load_dwordx4 s[4:7], s[74:75], 0x60
	s_load_dwordx2 s[10:11], s[74:75], 0x70
	v_lshl_or_b32 v4, s62, 6, v180
	v_ashrrev_i32_e32 v5, 31, v4
	v_lshlrev_b64 v[4:5], 2, v[4:5]
	s_waitcnt lgkmcnt(0)
	v_lshl_add_u64 v[6:7], s[4:5], 0, v[4:5]
	s_lshl_b32 s4, s62, 8
	v_lshl_add_u64 v[4:5], s[6:7], 0, v[4:5]
	s_ashr_i32 s5, s4, 31
	global_load_dword v3, v[6:7], off
	s_lshl_b64 s[4:5], s[4:5], 2
	global_load_dword v6, v[4:5], off
	s_add_u32 s4, s10, s4
	s_addc_u32 s5, s11, s5
	v_lshl_add_u64 v[4:5], v[180:181], 2, s[4:5]
	global_load_dword v7, v[4:5], off
	global_load_dword v8, v[4:5], off offset:256
	global_load_dword v9, v[4:5], off offset:512
	s_nop 0
	global_load_dword v4, v[4:5], off offset:768
	v_xor_b32_e32 v5, 1, v173
	v_cmp_lt_i32_e32 vcc, v2, v0
	v_xor_b32_e32 v10, 2, v173
	v_xor_b32_e32 v11, 4, v173
	v_cndmask_b32_e32 v2, v173, v2, vcc
	v_cmp_lt_i32_e32 vcc, v5, v0
	v_xor_b32_e32 v12, 8, v173
	v_xor_b32_e32 v13, 16, v173
	v_cndmask_b32_e32 v5, v173, v5, vcc
	v_cmp_lt_i32_e32 vcc, v10, v0
	v_lshlrev_b32_e32 v137, 2, v2
	v_lshlrev_b32_e32 v2, 2, v5
	v_cndmask_b32_e32 v10, v173, v10, vcc
	v_cmp_lt_i32_e32 vcc, v11, v0
	v_lshlrev_b32_e32 v5, 2, v10
	s_and_b64 s[16:17], s[76:77], exec
	v_cndmask_b32_e32 v11, v173, v11, vcc
	v_cmp_lt_i32_e32 vcc, v12, v0
	v_lshlrev_b32_e32 v10, 2, v11
	s_movk_i32 s1, 0x480
	v_cndmask_b32_e32 v12, v173, v12, vcc
	v_cmp_lt_i32_e32 vcc, v13, v0
	v_lshlrev_b32_e32 v11, 2, v12
	s_cselect_b32 s1, s1, 0x400
	v_cndmask_b32_e32 v0, v173, v13, vcc
	v_lshlrev_b32_e32 v0, 2, v0
	s_cmp_ge_i32 s2, s1
	s_waitcnt vmcnt(0)
	v_and_b32_e32 v12, 0x7fffffff, v3
	ds_bpermute_b32 v12, v2, v12
	v_and_b32_e32 v13, 0x7fffffff, v6
	ds_bpermute_b32 v2, v2, v13
	v_max_f32_e64 v3, |v3|, |v3|
	v_max_f32_e64 v6, |v6|, |v6|
	v_mul_f32_e32 v14, v9, v4
	v_mul_f32_e32 v13, v7, v8
	s_waitcnt lgkmcnt(0)
	v_max_f32_e32 v2, v2, v2
	v_mov_b32_dpp v14, v14 quad_perm:[1,0,3,2] row_mask:0xf bank_mask:0xf bound_ctrl:1
	v_fmac_f32_e32 v14, v9, v4
	v_max_f32_e32 v4, v12, v12
	v_max_f32_e32 v3, v3, v4
	v_max_f32_e32 v2, v6, v2
	ds_bpermute_b32 v4, v5, v3
	ds_bpermute_b32 v5, v5, v2
	v_mov_b32_dpp v13, v13 quad_perm:[1,0,3,2] row_mask:0xf bank_mask:0xf bound_ctrl:1
	v_fmac_f32_e32 v13, v7, v8
	v_add_f32_dpp v7, v14, v14 quad_perm:[2,3,0,1] row_mask:0xf bank_mask:0xf bound_ctrl:1
	s_waitcnt lgkmcnt(1)
	v_max_f32_e32 v4, v4, v4
	s_waitcnt lgkmcnt(0)
	v_max_f32_e32 v5, v5, v5
	v_max_f32_e32 v3, v3, v4
	v_max_f32_e32 v2, v2, v5
	ds_bpermute_b32 v4, v10, v3
	ds_bpermute_b32 v5, v10, v2
	v_add_f32_dpp v6, v13, v13 quad_perm:[2,3,0,1] row_mask:0xf bank_mask:0xf bound_ctrl:1
	v_add_f32_dpp v7, v7, v7 row_half_mirror row_mask:0xf bank_mask:0xf bound_ctrl:1
	s_waitcnt lgkmcnt(1)
	v_max_f32_e32 v4, v4, v4
	s_waitcnt lgkmcnt(0)
	v_max_f32_e32 v5, v5, v5
	v_max_f32_e32 v3, v3, v4
	v_max_f32_e32 v2, v2, v5
	ds_bpermute_b32 v4, v11, v3
	ds_bpermute_b32 v5, v11, v2
	v_add_f32_dpp v6, v6, v6 row_half_mirror row_mask:0xf bank_mask:0xf bound_ctrl:1
	v_add_f32_dpp v7, v7, v7 row_mirror row_mask:0xf bank_mask:0xf bound_ctrl:1
	s_waitcnt lgkmcnt(1)
	v_max_f32_e32 v4, v4, v4
	s_waitcnt lgkmcnt(0)
	v_max_f32_e32 v5, v5, v5
	v_max_f32_e32 v3, v3, v4
	v_max_f32_e32 v2, v2, v5
	ds_bpermute_b32 v4, v0, v3
	ds_bpermute_b32 v0, v0, v2
	v_add_f32_dpp v6, v6, v6 row_mirror row_mask:0xf bank_mask:0xf bound_ctrl:1
	v_readlane_b32 s3, v7, 0
	v_readlane_b32 s10, v6, 0
	s_waitcnt lgkmcnt(1)
	v_max_f32_e32 v4, v4, v4
	s_waitcnt lgkmcnt(0)
	v_max_f32_e32 v5, v0, v0
	v_max_f32_e32 v0, v3, v4
	v_max_f32_e32 v3, v2, v5
	ds_bpermute_b32 v2, v137, v0
	ds_bpermute_b32 v4, v137, v3
	v_readlane_b32 s11, v6, 16
	v_readlane_b32 s7, v6, 32
	v_readlane_b32 s14, v6, 48
	v_readlane_b32 s4, v7, 16
	v_readlane_b32 s5, v7, 32
	v_readlane_b32 s6, v7, 48
	s_cbranch_scc1 .LBB0_364
; #define LAS __attribute__((address_space(3)))
; __device__ __forceinline__ void attn_unit(const TI ti, CArgs& a, int b, int hd, int qrow0, int st_lo, int st_hi, float mfix, float lam, float lam_init, const float* subg, unsigned char* ldsg) {
;     const int tid = ti.tid, lane = tid & 63, w = tid >> 6, r = lane & 31, h = lane >> 5, qt = w >> 1, c = w & 1;
;     bf16_t* Qb = (bf16_t*)(a.ws + WS_Q); const bf16_t* Kb = (const bf16_t*)(a.ws + WS_K); const bf16_t* Vb = (const bf16_t*)(a.ws + WS_V);
;     LAS unsigned char* L = (LAS unsigned char*)ldsg;
;     constexpr int KOFF = 0, VOFF = 17408, BUFB = 35840;
;     bf16x8 qf[4];
;     { const bf16_t* qp = Qb + (size_t)(qrow0 + qt * 32 + r) * 1024 + hd * 128 + c * 64 + 8 * h;
; #pragma unroll
;       for (int ks = 0; ks < 4; ++ks) qf[ks] = *(const bf16x8*)(qp + 16 * ks); }
;     f32x16 O[4];
; #pragma unroll
;     for (int e = 0; e < 4; ++e)
; #pragma unroll
;         for (int i = 0; i < 16; ++i) O[e][i] = 0.f;
;     float lsum = 0.f;
;     u32x4 kreg[2], vreg[2];
;     typedef const __attribute__((address_space(1))) u32x4* gc16_t;
;     const int koff0 = (tid >> 4) * 1024 + (tid & 15) * 8, koff1 = koff0 + 32 * 1024, voff = lane * 1024 + w * 16;
; __device__ __forceinline__ void ph_attn(const TI ti, CArgs& a, int l, bool ctx_out, unsigned char* ldsg) {
;     ...
;     const float mfix = 8.f * mq * mk * 1.4426950408889634f * 1.03f;
;     const float* lp = a.in[14] + l * 256;
;     const float s1 = wave_sum(lp[lane] * lp[64 + lane]), s2 = wave_sum(lp[128 + lane] * lp[192 + lane]);
;     const float lam_init = 0.8f - 0.6f * expf(-0.3f * (float)l);
;     const float lam = expf(s1) - expf(s2) + lam_init;
;     const float* subg = a.in[15] + l * 128;
;     const int nun = 1024 + (ctx_out ? 128 : 0);
	v_cvt_f32_i32_e32 v5, s62
	s_mov_b32 s16, 0x3fb8aa3b
	s_waitcnt lgkmcnt(1)
	v_max_f32_e32 v2, v2, v2
	v_max_f32_e32 v0, v0, v0
	v_mul_f32_e32 v5, 0xbe99999a, v5
	v_mul_f32_e32 v6, 0x3fb8aa3b, v5
	v_fma_f32 v7, v5, s16, -v6
	v_rndne_f32_e32 v8, v6
	v_fmac_f32_e32 v7, 0x32a5705f, v5
	v_sub_f32_e32 v6, v6, v8
	v_add_f32_e32 v6, v6, v7
	v_cvt_i32_f32_e32 v8, v8
	v_exp_f32_e32 v6, v6
	v_mov_b32_e32 v7, s11
	v_add_f32_e32 v7, s10, v7
	s_mov_b32 s10, 0xc2ce8ed0
	v_ldexp_f32 v6, v6, v8
	v_mov_b32_e32 v8, s14
	v_add_f32_e32 v8, s7, v8
	v_add_f32_e32 v7, v7, v8
	v_mul_f32_e32 v8, 0x3fb8aa3b, v7
	v_fma_f32 v9, v7, s16, -v8
	v_rndne_f32_e32 v10, v8
	v_fmac_f32_e32 v9, 0x32a5705f, v7
	v_sub_f32_e32 v8, v8, v10
	v_add_f32_e32 v8, v8, v9
	v_exp_f32_e32 v8, v8
	v_cvt_i32_f32_e32 v9, v10
	v_cmp_ngt_f32_e32 vcc, s10, v5
	s_mov_b32 s7, 0x42b17218
	s_waitcnt lgkmcnt(0)
	v_max_f32_e32 v4, v4, v4
	v_cndmask_b32_e32 v6, 0, v6, vcc
	v_cmp_nlt_f32_e32 vcc, s7, v5
	v_max_f32_e32 v3, v3, v3
	v_max_f32_e32 v0, v0, v2
	v_cndmask_b32_e32 v5, v191, v6, vcc
	v_mov_b32_e32 v6, 0x3f4ccccd
	v_fmamk_f32 v18, v5, 0xbf19999a, v6
	v_ldexp_f32 v5, v8, v9
	v_mov_b32_e32 v6, s4
	v_mov_b32_e32 v8, s6
	v_add_f32_e32 v6, s3, v6
	v_add_f32_e32 v8, s5, v8
	v_add_f32_e32 v6, v6, v8
	v_mul_f32_e32 v8, 0x3fb8aa3b, v6
	v_fma_f32 v9, v6, s16, -v8
	v_rndne_f32_e32 v10, v8
	v_fmac_f32_e32 v9, 0x32a5705f, v6
	v_sub_f32_e32 v8, v8, v10
	v_add_f32_e32 v8, v8, v9
	v_exp_f32_e32 v8, v8
	v_cvt_i32_f32_e32 v9, v10
	v_cmp_ngt_f32_e32 vcc, s10, v7
	s_load_dwordx2 s[4:5], s[74:75], 0x78
	s_lshl_b32 s6, s62, 7
	v_cndmask_b32_e32 v5, 0, v5, vcc
	v_cmp_nlt_f32_e32 vcc, s7, v7
	v_ldexp_f32 v7, v8, v9
	v_max_f32_e32 v3, v3, v4
	v_cndmask_b32_e32 v5, v191, v5, vcc
	v_cmp_ngt_f32_e32 vcc, s10, v6
	s_load_dwordx2 s[10:11], s[74:75], 0x110
	v_mul_f32_e32 v0, 0x41000000, v0
	v_cndmask_b32_e32 v7, 0, v7, vcc
	v_cmp_nlt_f32_e32 vcc, s7, v6
	s_ashr_i32 s7, s6, 31
	s_lshl_b64 s[6:7], s[6:7], 2
	s_waitcnt lgkmcnt(0)
	s_add_u32 s4, s4, s6
	s_addc_u32 s5, s5, s7
	s_add_u32 s46, s10, 0xa600000
	s_addc_u32 s47, s11, 0
	s_add_u32 s3, s10, 0xca00000
	s_addc_u32 s6, s11, 0
	s_add_u32 s7, s10, 0xee00000
	v_lshlrev_b32_e32 v4, 3, v178
	v_mul_f32_e32 v0, v3, v0
	v_ashrrev_i32_e32 v3, 6, v178
	s_addc_u32 s10, s11, 0
	v_lshlrev_b32_e32 v2, 6, v178
	v_and_b32_e32 v4, 0x78, v4
	s_movk_i32 s11, 0xfc00
	v_and_or_b32 v140, v2, s11, v4
	v_lshlrev_b32_e32 v2, 4, v3
	v_lshl_add_u32 v142, v180, 10, v2
	v_lshlrev_b32_e32 v2, 4, v178
	v_and_b32_e32 v147, 0xf0, v2
	v_lshrrev_b32_e32 v2, 4, v178
	s_movk_i32 s14, 0x110
	v_mul_lo_u32 v155, v2, s14
	v_add_u32_e32 v2, 0x200, v178
	v_lshrrev_b32_e32 v2, 4, v2
	s_movk_i32 s11, 0x480
	v_cndmask_b32_e32 v6, v191, v7, vcc
	v_mul_lo_u32 v156, v2, s14
	v_mul_lo_u32 v2, v3, s11
	v_sub_f32_e32 v5, v5, v6
	v_lshlrev_b32_e32 v157, 1, v2
	v_lshlrev_b32_e32 v2, 1, v178
	v_lshrrev_b32_e32 v4, 1, v178
	v_add_f32_e32 v134, v18, v5
	v_lshrrev_b32_e32 v20, 5, v180
	v_and_b32_e32 v22, 1, v3
	v_and_b32_e32 v2, 8, v2
	v_and_b32_e32 v4, 4, v4
	v_and_b32_e32 v5, 51, v178
	v_mul_f32_e32 v0, 0x3fb8aa3b, v0
	v_lshlrev_b32_e32 v136, 6, v22
	v_lshlrev_b32_e32 v138, 3, v20
	v_or3_b32 v2, v2, v5, v4
	v_lshlrev_b32_e32 v158, 1, v2
	v_mul_f32_e32 v2, 0xbf83d70a, v0
	v_or_b32_e32 v0, v136, v138
	v_lshlrev_b32_e32 v144, 4, v20
	v_and_b32_e32 v19, 31, v178
	v_ashrrev_i32_e32 v21, 7, v178
	v_lshlrev_b32_e32 v161, 1, v0
	v_mov_b32_e32 v0, 0x3600
	s_movk_i32 s11, 0x90
	v_add_u32_e32 v166, 0, v144
	v_lshl_or_b32 v139, v21, 5, v19
	v_mad_u32_u24 v163, v19, s11, v0
	v_lshlrev_b32_e32 v0, 14, v21
	v_lshlrev_b32_e32 v21, 2, v180
	v_mov_b32_e32 v145, v1
	v_mad_u32_u24 v167, v19, s11, v166
	v_ashrrev_i32_e32 v141, 31, v140
	v_ashrrev_i32_e32 v143, 31, v142
	v_add_u32_e32 v154, 0, v147
	v_add3_u32 v159, 0, v157, v158
	v_cmp_lt_i32_e64 s[40:41], 3, v3
	v_mul_u32_u24_e32 v160, 0x110, v19
	v_mov_b32_e32 v3, v2
	v_mov_b32_e32 v4, v2
	v_mov_b32_e32 v5, v2
	v_mov_b32_e32 v6, v2
	v_mov_b32_e32 v7, v2
	v_mov_b32_e32 v8, v2
	v_mov_b32_e32 v9, v2
	v_mov_b32_e32 v10, v2
	v_mov_b32_e32 v11, v2
	v_mov_b32_e32 v12, v2
	v_mov_b32_e32 v13, v2
	v_mov_b32_e32 v14, v2
	v_mov_b32_e32 v15, v2
	v_mov_b32_e32 v16, v2
	v_mov_b32_e32 v17, v2
	v_mul_u32_u24_e32 v162, 0x90, v19
	v_cmp_eq_u32_e64 s[42:43], 0, v22
	v_cmp_eq_u32_e64 s[44:45], 1, v22
	v_add3_u32 v164, 0, v0, v21
	v_sub_f32_e32 v165, 1.0, v18
	v_lshlrev_b32_e32 v146, 2, v20
	v_lshl_add_u64 v[148:149], s[4:5], 0, v[144:145]
	v_readlane_b32 s98, v255, 42
	v_lshlrev_b32_e32 v250, 3, v180
	global_load_dwordx2 v[252:253], v250, s[4:5]
	s_lshl_b32 s98, s98, 9
	s_add_i32 s98, s98, 0x12000
	v_add_u32_e32 v250, s98, v250
	v_add_u32_e32 v249, s98, v144
	s_waitcnt vmcnt(0)
	ds_write_b64 v250, v[252:253]
	s_waitcnt lgkmcnt(0)
	v_mad_u32_u24 v145, v19, s14, 0
	v_add_u32_e32 v168, 0xc200, v167
	v_mov_b32_e32 v135, v134
	s_mov_b32 s16, s2
	s_cmp_lg_u32 s0, 0x100
	s_cbranch_scc1 .Lattn_noperm
	s_and_b32 s16, s2, 7
	s_lshl_b32 s16, s16, 5
	s_lshr_b32 s11, s2, 3
	s_or_b32 s16, s16, s11

; __device__ __forceinline__ unsigned pkbf(float lo, float hi) { f32x2 v = {lo, hi}; bf16x2v b = __builtin_convertvector(v, bf16x2v); return __builtin_bit_cast(unsigned, b); }
; __device__ __forceinline__ void attn_unit(const TI ti, CArgs& a, int b, int hd, int qrow0, int st_lo, int st_hi, float mfix, float lam, float lam_init, const float* subg, unsigned char* ldsg) {
;     ...
;     if (c == 0) {
;         float ssq = 0.f;
; #pragma unroll
;         for (int e = 0; e < 4; ++e)
; #pragma unroll
;             for (int i = 0; i < 16; ++i) { const float o = O[e][i] * linv - lam * X[(e * 16 + i) * 64 + lane]; O[e][i] = o; ssq += o * o; }
;         ssq += __shfl_xor(ssq, 32);
;         const float sc = rsqrtf(ssq * (1.f / 128.f) + 1e-6f) * (1.f - lam_init);
;         bf16_t* op = Qb + (size_t)(qrow0 + qt * 32 + r) * 1024 + hd * 128;
; #pragma unroll
;         for (int e = 0; e < 4; ++e)
; #pragma unroll
;             for (int g4 = 0; g4 < 4; ++g4) {
;                 const int e0 = e * 32 + 8 * g4 + 4 * h; const f32x4 sg = *(const f32x4*)(subg + e0);
;                 u32x2 o; o.x = pkbf(O[e][4 * g4 + 0] * sc * sg.x, O[e][4 * g4 + 1] * sc * sg.y); o.y = pkbf(O[e][4 * g4 + 2] * sc * sg.z, O[e][4 * g4 + 3] * sc * sg.w);
;                 *(u32x2*)(op + e0) = o;
.LBB0_346:
	s_or_b64 exec, exec, s[4:5]
	s_waitcnt lgkmcnt(0)
	s_barrier
	s_and_saveexec_b64 s[48:49], s[42:43]
	s_cbranch_execz .LBB0_348
	ds_read2st64_b32 v[90:91], v164 offset1:1
	ds_read2st64_b32 v[92:93], v164 offset0:2 offset1:3
	ds_read2st64_b32 v[94:95], v164 offset0:4 offset1:5
	ds_read2st64_b32 v[96:97], v164 offset0:6 offset1:7
	ds_read2st64_b32 v[98:99], v164 offset0:8 offset1:9
	ds_read2st64_b32 v[104:105], v164 offset0:10 offset1:11
	ds_read2st64_b32 v[108:109], v164 offset0:12 offset1:13
	ds_read2st64_b32 v[110:111], v164 offset0:14 offset1:15
	ds_read2st64_b32 v[112:113], v164 offset0:16 offset1:17
	ds_read2st64_b32 v[114:115], v164 offset0:18 offset1:19
	ds_read2st64_b32 v[116:117], v164 offset0:20 offset1:21
	ds_read2st64_b32 v[118:119], v164 offset0:22 offset1:23
	ds_read2st64_b32 v[120:121], v164 offset0:24 offset1:25
	ds_read2st64_b32 v[122:123], v164 offset0:26 offset1:27
	ds_read2st64_b32 v[124:125], v164 offset0:28 offset1:29
	ds_read2st64_b32 v[126:127], v164 offset0:30 offset1:31
	ds_read2st64_b32 v[128:129], v164 offset0:32 offset1:33
	ds_read2st64_b32 v[130:131], v164 offset0:34 offset1:35
	ds_read2st64_b32 v[132:133], v164 offset0:36 offset1:37
	ds_read2st64_b32 v[182:183], v164 offset0:38 offset1:39
	ds_read2st64_b32 v[184:185], v164 offset0:40 offset1:41
	ds_read2st64_b32 v[198:199], v164 offset0:42 offset1:43
	ds_read2st64_b32 v[200:201], v164 offset0:44 offset1:45
	ds_read2st64_b32 v[202:203], v164 offset0:46 offset1:47
	ds_read2st64_b32 v[204:205], v164 offset0:56 offset1:57
	ds_read2st64_b32 v[206:207], v164 offset0:58 offset1:59
	ds_read2st64_b32 v[82:83], v164 offset0:60 offset1:61
	ds_read2st64_b32 v[84:85], v164 offset0:62 offset1:63
	ds_read2st64_b32 v[208:209], v164 offset0:48 offset1:49
	ds_read2st64_b32 v[210:211], v164 offset0:50 offset1:51
	ds_read2st64_b32 v[212:213], v164 offset0:52 offset1:53
	ds_read2st64_b32 v[214:215], v164 offset0:54 offset1:55
	s_waitcnt lgkmcnt(14)
	v_pk_mul_f32 v[90:91], v[134:135], v[90:91]
	v_pk_mul_f32 v[92:93], v[134:135], v[92:93]
	v_pk_fma_f32 v[90:91], v[18:19], v[86:87], v[90:91] op_sel_hi:[1,0,1] neg_lo:[0,0,1] neg_hi:[0,0,1]
	v_pk_mul_f32 v[18:19], v[134:135], v[96:97]
	v_pk_fma_f32 v[20:21], v[20:21], v[86:87], v[92:93] op_sel_hi:[1,0,1] neg_lo:[0,0,1] neg_hi:[0,0,1]
	v_pk_fma_f32 v[92:93], v[24:25], v[86:87], v[18:19] op_sel_hi:[1,0,1] neg_lo:[0,0,1] neg_hi:[0,0,1]
	v_pk_mul_f32 v[18:19], v[134:135], v[94:95]
	s_waitcnt lgkmcnt(5)
	v_pk_mul_f32 v[82:83], v[134:135], v[82:83]
	v_pk_fma_f32 v[102:103], v[22:23], v[86:87], v[18:19] op_sel_hi:[1,0,1] neg_lo:[0,0,1] neg_hi:[0,0,1]
	v_pk_mul_f32 v[18:19], v[134:135], v[104:105]
	s_waitcnt lgkmcnt(1)
	v_pk_mul_f32 v[22:23], v[134:135], v[212:213]
	v_pk_fma_f32 v[94:95], v[28:29], v[86:87], v[18:19] op_sel_hi:[1,0,1] neg_lo:[0,0,1] neg_hi:[0,0,1]
	v_pk_mul_f32 v[18:19], v[134:135], v[98:99]
	v_pk_fma_f32 v[82:83], v[46:47], v[86:87], v[82:83] op_sel_hi:[1,0,1] neg_lo:[0,0,1] neg_hi:[0,0,1]
	v_pk_fma_f32 v[106:107], v[26:27], v[86:87], v[18:19] op_sel_hi:[1,0,1] neg_lo:[0,0,1] neg_hi:[0,0,1]
	v_pk_mul_f32 v[18:19], v[134:135], v[110:111]
	v_pk_mul_f32 v[46:47], v[134:135], v[84:85]
	v_pk_fma_f32 v[96:97], v[32:33], v[86:87], v[18:19] op_sel_hi:[1,0,1] neg_lo:[0,0,1] neg_hi:[0,0,1]
	v_pk_mul_f32 v[18:19], v[134:135], v[108:109]
	v_pk_mul_f32 v[218:219], v[90:91], v[90:91]
	v_pk_fma_f32 v[108:109], v[30:31], v[86:87], v[18:19] op_sel_hi:[1,0,1] neg_lo:[0,0,1] neg_hi:[0,0,1]
	v_pk_mul_f32 v[18:19], v[134:135], v[114:115]
	v_pk_fma_f32 v[84:85], v[48:49], v[86:87], v[46:47] op_sel_hi:[1,0,1] neg_lo:[0,0,1] neg_hi:[0,0,1]
	v_pk_fma_f32 v[98:99], v[68:69], v[86:87], v[18:19] op_sel_hi:[1,0,1] neg_lo:[0,0,1] neg_hi:[0,0,1]
	v_pk_mul_f32 v[18:19], v[134:135], v[112:113]
	ds_read_b128 v[46:49], v249
	v_pk_fma_f32 v[104:105], v[66:67], v[86:87], v[18:19] op_sel_hi:[1,0,1] neg_lo:[0,0,1] neg_hi:[0,0,1]
	v_pk_mul_f32 v[18:19], v[134:135], v[118:119]
	v_pk_mul_f32 v[216:217], v[20:21], v[20:21]
	v_pk_fma_f32 v[32:33], v[72:73], v[86:87], v[18:19] op_sel_hi:[1,0,1] neg_lo:[0,0,1] neg_hi:[0,0,1]
	v_pk_mul_f32 v[18:19], v[134:135], v[116:117]
	v_pk_mul_f32 v[222:223], v[102:103], v[102:103]
	v_pk_fma_f32 v[70:71], v[70:71], v[86:87], v[18:19] op_sel_hi:[1,0,1] neg_lo:[0,0,1] neg_hi:[0,0,1]
	v_pk_mul_f32 v[18:19], v[134:135], v[122:123]
	v_pk_mul_f32 v[220:221], v[92:93], v[92:93]
	v_pk_fma_f32 v[66:67], v[76:77], v[86:87], v[18:19] op_sel_hi:[1,0,1] neg_lo:[0,0,1] neg_hi:[0,0,1]
	v_pk_mul_f32 v[18:19], v[134:135], v[120:121]
	v_pk_mul_f32 v[226:227], v[106:107], v[106:107]
	v_pk_fma_f32 v[72:73], v[74:75], v[86:87], v[18:19] op_sel_hi:[1,0,1] neg_lo:[0,0,1] neg_hi:[0,0,1]
	v_pk_mul_f32 v[18:19], v[134:135], v[126:127]
	v_pk_mul_f32 v[224:225], v[94:95], v[94:95]
	v_pk_fma_f32 v[68:69], v[80:81], v[86:87], v[18:19] op_sel_hi:[1,0,1] neg_lo:[0,0,1] neg_hi:[0,0,1]
	v_pk_mul_f32 v[18:19], v[134:135], v[124:125]
	v_pk_mul_f32 v[228:229], v[108:109], v[108:109]
	v_pk_fma_f32 v[74:75], v[78:79], v[86:87], v[18:19] op_sel_hi:[1,0,1] neg_lo:[0,0,1] neg_hi:[0,0,1]
	v_pk_mul_f32 v[18:19], v[134:135], v[130:131]
	v_pk_mul_f32 v[110:111], v[96:97], v[96:97]
	v_pk_fma_f32 v[52:53], v[52:53], v[86:87], v[18:19] op_sel_hi:[1,0,1] neg_lo:[0,0,1] neg_hi:[0,0,1]
	v_pk_mul_f32 v[18:19], v[134:135], v[128:129]
	v_pk_mul_f32 v[112:113], v[104:105], v[104:105]
	v_pk_fma_f32 v[50:51], v[50:51], v[86:87], v[18:19] op_sel_hi:[1,0,1] neg_lo:[0,0,1] neg_hi:[0,0,1]
	v_pk_mul_f32 v[18:19], v[134:135], v[182:183]
	v_pk_mul_f32 v[114:115], v[98:99], v[98:99]
	v_pk_fma_f32 v[24:25], v[56:57], v[86:87], v[18:19] op_sel_hi:[1,0,1] neg_lo:[0,0,1] neg_hi:[0,0,1]
; __device__ __forceinline__ unsigned pkbf(float lo, float hi) { f32x2 v = {lo, hi}; bf16x2v b = __builtin_convertvector(v, bf16x2v); return __builtin_bit_cast(unsigned, b); }
; __device__ __forceinline__ void attn_unit(const TI ti, CArgs& a, int b, int hd, int qrow0, int st_lo, int st_hi, float mfix, float lam, float lam_init, const float* subg, unsigned char* ldsg) {
;     ...
;             for (int i = 0; i < 16; ++i) { const float o = O[e][i] * linv - lam * X[(e * 16 + i) * 64 + lane]; O[e][i] = o; ssq += o * o; }
;         ssq += __shfl_xor(ssq, 32);
;         const float sc = rsqrtf(ssq * (1.f / 128.f) + 1e-6f) * (1.f - lam_init);
;         bf16_t* op = Qb + (size_t)(qrow0 + qt * 32 + r) * 1024 + hd * 128;
; #pragma unroll
;         for (int e = 0; e < 4; ++e)
; #pragma unroll
;             for (int g4 = 0; g4 < 4; ++g4) {
;                 const int e0 = e * 32 + 8 * g4 + 4 * h; const f32x4 sg = *(const f32x4*)(subg + e0);
;                 u32x2 o; o.x = pkbf(O[e][4 * g4 + 0] * sc * sg.x, O[e][4 * g4 + 1] * sc * sg.y); o.y = pkbf(O[e][4 * g4 + 2] * sc * sg.z, O[e][4 * g4 + 3] * sc * sg.w);
;                 *(u32x2*)(op + e0) = o;
	v_pk_mul_f32 v[18:19], v[134:135], v[132:133]
	v_pk_mul_f32 v[116:117], v[70:71], v[70:71]
	v_pk_fma_f32 v[54:55], v[54:55], v[86:87], v[18:19] op_sel_hi:[1,0,1] neg_lo:[0,0,1] neg_hi:[0,0,1]
	v_pk_mul_f32 v[18:19], v[134:135], v[198:199]
	v_pk_mul_f32 v[118:119], v[32:33], v[32:33]
	v_pk_fma_f32 v[26:27], v[60:61], v[86:87], v[18:19] op_sel_hi:[1,0,1] neg_lo:[0,0,1] neg_hi:[0,0,1]
	v_pk_mul_f32 v[18:19], v[134:135], v[184:185]
	v_pk_mul_f32 v[120:121], v[72:73], v[72:73]
	v_pk_fma_f32 v[56:57], v[58:59], v[86:87], v[18:19] op_sel_hi:[1,0,1] neg_lo:[0,0,1] neg_hi:[0,0,1]
	v_pk_mul_f32 v[18:19], v[134:135], v[202:203]
	v_pk_mul_f32 v[76:77], v[66:67], v[66:67]
	v_pk_fma_f32 v[28:29], v[64:65], v[86:87], v[18:19] op_sel_hi:[1,0,1] neg_lo:[0,0,1] neg_hi:[0,0,1]
	v_pk_mul_f32 v[18:19], v[134:135], v[200:201]
	v_pk_mul_f32 v[78:79], v[74:75], v[74:75]
	v_pk_fma_f32 v[58:59], v[62:63], v[86:87], v[18:19] op_sel_hi:[1,0,1] neg_lo:[0,0,1] neg_hi:[0,0,1]
	v_pk_mul_f32 v[18:19], v[134:135], v[210:211]
	v_pk_mul_f32 v[80:81], v[68:69], v[68:69]
	v_pk_fma_f32 v[30:31], v[36:37], v[86:87], v[18:19] op_sel_hi:[1,0,1] neg_lo:[0,0,1] neg_hi:[0,0,1]
	v_pk_mul_f32 v[18:19], v[134:135], v[208:209]
	v_pk_fma_f32 v[36:37], v[38:39], v[86:87], v[22:23] op_sel_hi:[1,0,1] neg_lo:[0,0,1] neg_hi:[0,0,1]
	v_pk_fma_f32 v[34:35], v[34:35], v[86:87], v[18:19] op_sel_hi:[1,0,1] neg_lo:[0,0,1] neg_hi:[0,0,1]
	s_waitcnt lgkmcnt(0)
	v_pk_mul_f32 v[18:19], v[134:135], v[214:215]
	v_pk_mul_f32 v[22:23], v[134:135], v[206:207]
	v_pk_mul_f32 v[38:39], v[134:135], v[204:205]
	v_pk_fma_f32 v[18:19], v[40:41], v[86:87], v[18:19] op_sel_hi:[1,0,1] neg_lo:[0,0,1] neg_hi:[0,0,1]
	v_pk_fma_f32 v[22:23], v[44:45], v[86:87], v[22:23] op_sel_hi:[1,0,1] neg_lo:[0,0,1] neg_hi:[0,0,1]
	v_pk_fma_f32 v[38:39], v[42:43], v[86:87], v[38:39] op_sel_hi:[1,0,1] neg_lo:[0,0,1] neg_hi:[0,0,1]
	v_add_f32_e32 v86, v218, v219
	v_add_f32_e32 v86, v86, v216
	v_add_f32_e32 v86, v86, v217
	v_add_f32_e32 v86, v86, v222
	v_add_f32_e32 v86, v86, v223
	v_add_f32_e32 v86, v86, v220
	v_add_f32_e32 v86, v86, v221
	v_add_f32_e32 v86, v86, v226
	v_add_f32_e32 v86, v86, v227
	v_add_f32_e32 v86, v86, v224
	v_add_f32_e32 v86, v86, v225
	v_add_f32_e32 v86, v86, v228
	v_add_f32_e32 v86, v86, v229
	v_add_f32_e32 v86, v86, v110
	v_add_f32_e32 v86, v86, v111
	v_add_f32_e32 v86, v86, v112
	v_add_f32_e32 v86, v86, v113
	v_add_f32_e32 v86, v86, v114
	v_add_f32_e32 v86, v86, v115
	v_add_f32_e32 v86, v86, v116
	v_add_f32_e32 v86, v86, v117
	v_add_f32_e32 v86, v86, v118
	v_add_f32_e32 v86, v86, v119
	v_add_f32_e32 v86, v86, v120
	v_add_f32_e32 v86, v86, v121
	v_add_f32_e32 v76, v86, v76
	v_add_f32_e32 v76, v76, v77
	v_add_f32_e32 v76, v76, v78
	v_add_f32_e32 v76, v76, v79
	v_add_f32_e32 v76, v76, v80
	v_pk_mul_f32 v[124:125], v[50:51], v[50:51]
	v_add_f32_e32 v76, v76, v81
	v_add_f32_e32 v76, v76, v124
	v_pk_mul_f32 v[122:123], v[52:53], v[52:53]
	v_add_f32_e32 v76, v76, v125
	v_add_f32_e32 v76, v76, v122
	v_pk_mul_f32 v[128:129], v[54:55], v[54:55]
	v_add_f32_e32 v76, v76, v123
	v_add_f32_e32 v76, v76, v128
	v_pk_mul_f32 v[126:127], v[24:25], v[24:25]
	v_add_f32_e32 v76, v76, v129
	v_add_f32_e32 v76, v76, v126
	v_pk_mul_f32 v[130:131], v[56:57], v[56:57]
	v_add_f32_e32 v76, v76, v127
	v_add_f32_e32 v76, v76, v130
	v_pk_mul_f32 v[60:61], v[26:27], v[26:27]
	v_add_f32_e32 v76, v76, v131
	v_add_f32_e32 v60, v76, v60
	v_pk_mul_f32 v[62:63], v[58:59], v[58:59]
	v_add_f32_e32 v60, v60, v61
	v_add_f32_e32 v60, v60, v62
	v_pk_mul_f32 v[64:65], v[28:29], v[28:29]
	v_add_f32_e32 v60, v60, v63
	v_add_f32_e32 v60, v60, v64
	v_pk_mul_f32 v[182:183], v[34:35], v[34:35]
	v_add_f32_e32 v60, v60, v65
	v_add_f32_e32 v60, v60, v182
	v_pk_mul_f32 v[132:133], v[30:31], v[30:31]
	v_add_f32_e32 v60, v60, v183
	v_add_f32_e32 v60, v60, v132
	v_pk_mul_f32 v[184:185], v[36:37], v[36:37]
	v_add_f32_e32 v60, v60, v133
	v_add_f32_e32 v60, v60, v184
	v_pk_mul_f32 v[40:41], v[18:19], v[18:19]
	v_add_f32_e32 v60, v60, v185
	v_add_f32_e32 v40, v60, v40
	v_pk_mul_f32 v[42:43], v[38:39], v[38:39]
	v_add_f32_e32 v40, v40, v41
	v_add_f32_e32 v40, v40, v42
	v_pk_mul_f32 v[44:45], v[22:23], v[22:23]
	v_add_f32_e32 v40, v40, v43
	v_add_f32_e32 v40, v40, v44
	v_pk_mul_f32 v[88:89], v[82:83], v[82:83]
	v_add_f32_e32 v40, v40, v45
	v_add_f32_e32 v40, v40, v88
	v_pk_mul_f32 v[100:101], v[84:85], v[84:85]
	v_add_f32_e32 v40, v40, v89
	v_add_f32_e32 v40, v40, v100
	v_add_f32_e32 v40, v40, v101
	ds_bpermute_b32 v41, v137, v40
	s_waitcnt lgkmcnt(0)
	v_add_f32_e32 v40, v40, v41
	v_fmamk_f32 v40, v40, 0x3c000000, v172
	v_mul_f32_e32 v41, 0x4b800000, v40
	v_cmp_gt_f32_e32 vcc, s8, v40
	s_nop 1
	v_cndmask_b32_e32 v40, v40, v41, vcc
	v_rsq_f32_e32 v42, v40
	v_lshlrev_b32_e32 v40, 1, v146
	v_mov_b32_e32 v41, v1
	v_lshl_add_u64 v[44:45], v[152:153], 0, v[40:41]
	v_mul_f32_e32 v40, 0x45800000, v42
	v_cndmask_b32_e32 v40, v42, v40, vcc
	v_mul_f32_e32 v60, v165, v40
	v_pk_mul_f32 v[40:41], v[90:91], v[60:61] op_sel_hi:[1,0]
	v_pk_mul_f32 v[20:21], v[20:21], v[60:61] op_sel_hi:[1,0]
	s_waitcnt lgkmcnt(0)
	v_pk_mul_f32 v[40:41], v[46:47], v[40:41]
	v_pk_mul_f32 v[20:21], v[48:49], v[20:21]
	v_cvt_pk_bf16_f32 v40, v40, v41
	v_cvt_pk_bf16_f32 v41, v20, v21
	global_store_dwordx2 v[44:45], v[40:41], off
	ds_read_b128 v[40:43], v249 offset:32
	v_pk_mul_f32 v[20:21], v[102:103], v[60:61] op_sel_hi:[1,0]
	v_pk_mul_f32 v[46:47], v[94:95], v[60:61] op_sel_hi:[1,0]
	v_pk_mul_f32 v[32:33], v[32:33], v[60:61] op_sel_hi:[1,0]
	v_pk_mul_f32 v[24:25], v[24:25], v[60:61] op_sel_hi:[1,0]
	v_pk_mul_f32 v[28:29], v[28:29], v[60:61] op_sel_hi:[1,0]
	v_pk_mul_f32 v[18:19], v[18:19], v[60:61] op_sel_hi:[1,0]
	v_pk_mul_f32 v[22:23], v[22:23], v[60:61] op_sel_hi:[1,0]
	s_waitcnt lgkmcnt(0)
; __device__ __forceinline__ unsigned pkbf(float lo, float hi) { f32x2 v = {lo, hi}; bf16x2v b = __builtin_convertvector(v, bf16x2v); return __builtin_bit_cast(unsigned, b); }
; __device__ __forceinline__ void attn_unit(const TI ti, CArgs& a, int b, int hd, int qrow0, int st_lo, int st_hi, float mfix, float lam, float lam_init, const float* subg, unsigned char* ldsg) {
;     ...
; #pragma unroll
;         for (int e = 0; e < 4; ++e)
; #pragma unroll
;             for (int g4 = 0; g4 < 4; ++g4) {
;                 const int e0 = e * 32 + 8 * g4 + 4 * h; const f32x4 sg = *(const f32x4*)(subg + e0);
;                 u32x2 o; o.x = pkbf(O[e][4 * g4 + 0] * sc * sg.x, O[e][4 * g4 + 1] * sc * sg.y); o.y = pkbf(O[e][4 * g4 + 2] * sc * sg.z, O[e][4 * g4 + 3] * sc * sg.w);
;                 *(u32x2*)(op + e0) = o;
;             }
	v_pk_mul_f32 v[20:21], v[40:41], v[20:21]
	v_pk_mul_f32 v[40:41], v[92:93], v[60:61] op_sel_hi:[1,0]
	v_cvt_pk_bf16_f32 v20, v20, v21
	v_pk_mul_f32 v[40:41], v[42:43], v[40:41]
	s_nop 0
	v_cvt_pk_bf16_f32 v21, v40, v41
	global_store_dwordx2 v[44:45], v[20:21], off offset:16
	ds_read_b128 v[40:43], v249 offset:64
	v_pk_mul_f32 v[20:21], v[106:107], v[60:61] op_sel_hi:[1,0]
	s_waitcnt lgkmcnt(0)
	v_pk_mul_f32 v[20:21], v[40:41], v[20:21]
	v_pk_mul_f32 v[40:41], v[42:43], v[46:47]
	v_cvt_pk_bf16_f32 v20, v20, v21
	v_cvt_pk_bf16_f32 v21, v40, v41
	global_store_dwordx2 v[44:45], v[20:21], off offset:32
	ds_read_b128 v[40:43], v249 offset:96
	v_pk_mul_f32 v[20:21], v[108:109], v[60:61] op_sel_hi:[1,0]
	v_pk_mul_f32 v[46:47], v[96:97], v[60:61] op_sel_hi:[1,0]
	s_waitcnt lgkmcnt(0)
	v_pk_mul_f32 v[20:21], v[40:41], v[20:21]
	v_pk_mul_f32 v[40:41], v[42:43], v[46:47]
	v_cvt_pk_bf16_f32 v20, v20, v21
	v_cvt_pk_bf16_f32 v21, v40, v41
	global_store_dwordx2 v[44:45], v[20:21], off offset:48
	ds_read_b128 v[40:43], v249 offset:128
	v_pk_mul_f32 v[20:21], v[104:105], v[60:61] op_sel_hi:[1,0]
	v_pk_mul_f32 v[46:47], v[98:99], v[60:61] op_sel_hi:[1,0]
	s_waitcnt lgkmcnt(0)
	v_pk_mul_f32 v[20:21], v[40:41], v[20:21]
	v_pk_mul_f32 v[40:41], v[42:43], v[46:47]
	v_cvt_pk_bf16_f32 v20, v20, v21
	v_cvt_pk_bf16_f32 v21, v40, v41
	global_store_dwordx2 v[44:45], v[20:21], off offset:64
	ds_read_b128 v[40:43], v249 offset:160
	v_pk_mul_f32 v[20:21], v[70:71], v[60:61] op_sel_hi:[1,0]
	s_waitcnt lgkmcnt(0)
	v_pk_mul_f32 v[32:33], v[42:43], v[32:33]
	v_pk_mul_f32 v[20:21], v[40:41], v[20:21]
	s_nop 0
	v_cvt_pk_bf16_f32 v20, v20, v21
	v_cvt_pk_bf16_f32 v21, v32, v33
	global_store_dwordx2 v[44:45], v[20:21], off offset:80
	ds_read_b128 v[40:43], v249 offset:192
	v_pk_mul_f32 v[20:21], v[72:73], v[60:61] op_sel_hi:[1,0]
	v_pk_mul_f32 v[32:33], v[66:67], v[60:61] op_sel_hi:[1,0]
	s_waitcnt lgkmcnt(0)
	v_pk_mul_f32 v[20:21], v[40:41], v[20:21]
	v_pk_mul_f32 v[32:33], v[42:43], v[32:33]
	v_cvt_pk_bf16_f32 v20, v20, v21
	v_cvt_pk_bf16_f32 v21, v32, v33
	global_store_dwordx2 v[44:45], v[20:21], off offset:96
	ds_read_b128 v[40:43], v249 offset:224
	v_pk_mul_f32 v[20:21], v[74:75], v[60:61] op_sel_hi:[1,0]
	v_pk_mul_f32 v[32:33], v[68:69], v[60:61] op_sel_hi:[1,0]
	s_waitcnt lgkmcnt(0)
	v_pk_mul_f32 v[20:21], v[20:21], v[40:41]
	v_pk_mul_f32 v[32:33], v[32:33], v[42:43]
	v_cvt_pk_bf16_f32 v20, v20, v21
	v_cvt_pk_bf16_f32 v21, v32, v33
	global_store_dwordx2 v[44:45], v[20:21], off offset:112
	ds_read_b128 v[40:43], v249 offset:256
	v_pk_mul_f32 v[20:21], v[50:51], v[60:61] op_sel_hi:[1,0]
	v_pk_mul_f32 v[32:33], v[52:53], v[60:61] op_sel_hi:[1,0]
	s_waitcnt lgkmcnt(0)
	v_pk_mul_f32 v[20:21], v[20:21], v[40:41]
	v_pk_mul_f32 v[32:33], v[32:33], v[42:43]
	v_cvt_pk_bf16_f32 v20, v20, v21
	v_cvt_pk_bf16_f32 v21, v32, v33
	global_store_dwordx2 v[44:45], v[20:21], off offset:128
	ds_read_b128 v[40:43], v249 offset:288
	v_pk_mul_f32 v[20:21], v[54:55], v[60:61] op_sel_hi:[1,0]
	s_waitcnt lgkmcnt(0)
	v_pk_mul_f32 v[24:25], v[24:25], v[42:43]
	v_pk_mul_f32 v[20:21], v[20:21], v[40:41]
	s_nop 0
	v_cvt_pk_bf16_f32 v20, v20, v21
	v_cvt_pk_bf16_f32 v21, v24, v25
	global_store_dwordx2 v[44:45], v[20:21], off offset:144
	ds_read_b128 v[40:43], v249 offset:320
	v_pk_mul_f32 v[20:21], v[56:57], v[60:61] op_sel_hi:[1,0]
	v_pk_mul_f32 v[24:25], v[26:27], v[60:61] op_sel_hi:[1,0]
	s_waitcnt lgkmcnt(0)
	v_pk_mul_f32 v[20:21], v[20:21], v[40:41]
	v_pk_mul_f32 v[24:25], v[24:25], v[42:43]
	v_cvt_pk_bf16_f32 v20, v20, v21
	v_cvt_pk_bf16_f32 v21, v24, v25
	global_store_dwordx2 v[44:45], v[20:21], off offset:160
	ds_read_b128 v[24:27], v249 offset:352
	v_pk_mul_f32 v[20:21], v[58:59], v[60:61] op_sel_hi:[1,0]
	s_waitcnt lgkmcnt(0)
	v_pk_mul_f32 v[20:21], v[20:21], v[24:25]
	v_pk_mul_f32 v[24:25], v[28:29], v[26:27]
	v_cvt_pk_bf16_f32 v20, v20, v21
	v_cvt_pk_bf16_f32 v21, v24, v25
	global_store_dwordx2 v[44:45], v[20:21], off offset:176
	ds_read_b128 v[24:27], v249 offset:384
	v_pk_mul_f32 v[20:21], v[34:35], v[60:61] op_sel_hi:[1,0]
	v_pk_mul_f32 v[28:29], v[30:31], v[60:61] op_sel_hi:[1,0]
	s_waitcnt lgkmcnt(0)
	v_pk_mul_f32 v[20:21], v[20:21], v[24:25]
	v_pk_mul_f32 v[24:25], v[28:29], v[26:27]
	v_cvt_pk_bf16_f32 v20, v20, v21
	v_cvt_pk_bf16_f32 v21, v24, v25
	global_store_dwordx2 v[44:45], v[20:21], off offset:192
	ds_read_b128 v[24:27], v249 offset:416
	v_pk_mul_f32 v[20:21], v[36:37], v[60:61] op_sel_hi:[1,0]
	s_waitcnt lgkmcnt(0)
	v_pk_mul_f32 v[18:19], v[18:19], v[26:27]
	v_pk_mul_f32 v[20:21], v[20:21], v[24:25]
	v_pk_mul_f32 v[24:25], v[38:39], v[60:61] op_sel_hi:[1,0]
	v_cvt_pk_bf16_f32 v20, v20, v21
	v_cvt_pk_bf16_f32 v21, v18, v19
	global_store_dwordx2 v[44:45], v[20:21], off offset:208
	ds_read_b128 v[18:21], v249 offset:448
	s_waitcnt lgkmcnt(0)
	v_pk_mul_f32 v[18:19], v[24:25], v[18:19]
	v_pk_mul_f32 v[20:21], v[22:23], v[20:21]
	v_cvt_pk_bf16_f32 v18, v18, v19
	v_cvt_pk_bf16_f32 v19, v20, v21
	global_store_dwordx2 v[44:45], v[18:19], off offset:224
	ds_read_b128 v[18:21], v249 offset:480
	v_pk_mul_f32 v[22:23], v[82:83], v[60:61] op_sel_hi:[1,0]
	v_pk_mul_f32 v[24:25], v[84:85], v[60:61] op_sel_hi:[1,0]
	s_waitcnt lgkmcnt(0)
	v_pk_mul_f32 v[18:19], v[22:23], v[18:19]
	v_pk_mul_f32 v[20:21], v[24:25], v[20:21]
	v_cvt_pk_bf16_f32 v18, v18, v19
	v_cvt_pk_bf16_f32 v19, v20, v21
	global_store_dwordx2 v[44:45], v[18:19], off offset:240

; __device__ __forceinline__ unsigned pkbf(float lo, float hi) { f32x2 v = {lo, hi}; bf16x2v b = __builtin_convertvector(v, bf16x2v); return __builtin_bit_cast(unsigned, b); }
; __device__ __forceinline__ void attn_unit(const TI ti, CArgs& a, int b, int hd, int qrow0, int st_lo, int st_hi, float mfix, float lam, float lam_init, const float* subg, unsigned char* ldsg) {
;     ...
;     if (c == 0) {
;         float ssq = 0.f;
; #pragma unroll
;         for (int e = 0; e < 4; ++e)
; #pragma unroll
;             for (int i = 0; i < 16; ++i) { const float o = O[e][i] * linv - lam * X[(e * 16 + i) * 64 + lane]; O[e][i] = o; ssq += o * o; }
;         ssq += __shfl_xor(ssq, 32);
;         const float sc = rsqrtf(ssq * (1.f / 128.f) + 1e-6f) * (1.f - lam_init);
;         bf16_t* op = Qb + (size_t)(qrow0 + qt * 32 + r) * 1024 + hd * 128;
; #pragma unroll
;         for (int e = 0; e < 4; ++e)
; #pragma unroll
;             for (int g4 = 0; g4 < 4; ++g4) {
;                 const int e0 = e * 32 + 8 * g4 + 4 * h; const f32x4 sg = *(const f32x4*)(subg + e0);
;                 u32x2 o; o.x = pkbf(O[e][4 * g4 + 0] * sc * sg.x, O[e][4 * g4 + 1] * sc * sg.y); o.y = pkbf(O[e][4 * g4 + 2] * sc * sg.z, O[e][4 * g4 + 3] * sc * sg.w);
;                 *(u32x2*)(op + e0) = o;
.LBB0_362:
	s_or_b64 exec, exec, s[4:5]
	s_waitcnt lgkmcnt(0)
	s_barrier
	s_and_saveexec_b64 s[48:49], s[42:43]
	s_cbranch_execz .LBB0_331
	ds_read2st64_b32 v[88:89], v164 offset1:1
	ds_read2st64_b32 v[90:91], v164 offset0:2 offset1:3
	ds_read2st64_b32 v[92:93], v164 offset0:4 offset1:5
	ds_read2st64_b32 v[94:95], v164 offset0:6 offset1:7
	ds_read2st64_b32 v[96:97], v164 offset0:8 offset1:9
	ds_read2st64_b32 v[102:103], v164 offset0:10 offset1:11
	ds_read2st64_b32 v[104:105], v164 offset0:12 offset1:13
	ds_read2st64_b32 v[106:107], v164 offset0:14 offset1:15
	ds_read2st64_b32 v[108:109], v164 offset0:16 offset1:17
	ds_read2st64_b32 v[114:115], v164 offset0:18 offset1:19
	ds_read2st64_b32 v[116:117], v164 offset0:20 offset1:21
	ds_read2st64_b32 v[118:119], v164 offset0:22 offset1:23
	ds_read2st64_b32 v[120:121], v164 offset0:24 offset1:25
	ds_read2st64_b32 v[122:123], v164 offset0:26 offset1:27
	ds_read2st64_b32 v[124:125], v164 offset0:28 offset1:29
	ds_read2st64_b32 v[126:127], v164 offset0:30 offset1:31
	ds_read2st64_b32 v[128:129], v164 offset0:32 offset1:33
	ds_read2st64_b32 v[130:131], v164 offset0:34 offset1:35
	ds_read2st64_b32 v[132:133], v164 offset0:36 offset1:37
	ds_read2st64_b32 v[150:151], v164 offset0:38 offset1:39
	ds_read2st64_b32 v[170:171], v164 offset0:40 offset1:41
	ds_read2st64_b32 v[182:183], v164 offset0:42 offset1:43
	ds_read2st64_b32 v[184:185], v164 offset0:44 offset1:45
	ds_read2st64_b32 v[198:199], v164 offset0:46 offset1:47
	ds_read2st64_b32 v[200:201], v164 offset0:56 offset1:57
	ds_read2st64_b32 v[202:203], v164 offset0:58 offset1:59
	ds_read2st64_b32 v[82:83], v164 offset0:60 offset1:61
	ds_read2st64_b32 v[84:85], v164 offset0:62 offset1:63
	ds_read2st64_b32 v[204:205], v164 offset0:48 offset1:49
	ds_read2st64_b32 v[206:207], v164 offset0:50 offset1:51
	ds_read2st64_b32 v[208:209], v164 offset0:52 offset1:53
	ds_read2st64_b32 v[210:211], v164 offset0:54 offset1:55
	s_waitcnt lgkmcnt(14)
	v_pk_mul_f32 v[88:89], v[134:135], v[88:89]
	v_pk_mul_f32 v[90:91], v[134:135], v[90:91]
	v_pk_fma_f32 v[88:89], v[18:19], v[0:1], v[88:89] op_sel_hi:[1,0,1] neg_lo:[0,0,1] neg_hi:[0,0,1]
	v_pk_mul_f32 v[18:19], v[134:135], v[94:95]
	v_pk_fma_f32 v[20:21], v[20:21], v[0:1], v[90:91] op_sel_hi:[1,0,1] neg_lo:[0,0,1] neg_hi:[0,0,1]
	v_pk_fma_f32 v[90:91], v[24:25], v[0:1], v[18:19] op_sel_hi:[1,0,1] neg_lo:[0,0,1] neg_hi:[0,0,1]
	v_pk_mul_f32 v[18:19], v[134:135], v[92:93]
	s_waitcnt lgkmcnt(5)
	v_pk_mul_f32 v[82:83], v[134:135], v[82:83]
	v_pk_fma_f32 v[100:101], v[22:23], v[0:1], v[18:19] op_sel_hi:[1,0,1] neg_lo:[0,0,1] neg_hi:[0,0,1]
	v_pk_mul_f32 v[18:19], v[134:135], v[102:103]
	s_waitcnt lgkmcnt(1)
	v_pk_mul_f32 v[22:23], v[134:135], v[208:209]
	v_pk_fma_f32 v[92:93], v[28:29], v[0:1], v[18:19] op_sel_hi:[1,0,1] neg_lo:[0,0,1] neg_hi:[0,0,1]
	v_pk_mul_f32 v[18:19], v[134:135], v[96:97]
	v_pk_fma_f32 v[82:83], v[62:63], v[0:1], v[82:83] op_sel_hi:[1,0,1] neg_lo:[0,0,1] neg_hi:[0,0,1]
	v_pk_fma_f32 v[110:111], v[26:27], v[0:1], v[18:19] op_sel_hi:[1,0,1] neg_lo:[0,0,1] neg_hi:[0,0,1]
	v_pk_mul_f32 v[18:19], v[134:135], v[106:107]
	v_pk_mul_f32 v[62:63], v[134:135], v[84:85]
	v_pk_fma_f32 v[94:95], v[32:33], v[0:1], v[18:19] op_sel_hi:[1,0,1] neg_lo:[0,0,1] neg_hi:[0,0,1]
	v_pk_mul_f32 v[18:19], v[134:135], v[104:105]
	v_pk_mul_f32 v[214:215], v[88:89], v[88:89]
	v_pk_fma_f32 v[112:113], v[30:31], v[0:1], v[18:19] op_sel_hi:[1,0,1] neg_lo:[0,0,1] neg_hi:[0,0,1]
	v_pk_mul_f32 v[18:19], v[134:135], v[114:115]
	v_pk_fma_f32 v[84:85], v[64:65], v[0:1], v[62:63] op_sel_hi:[1,0,1] neg_lo:[0,0,1] neg_hi:[0,0,1]
	v_pk_fma_f32 v[96:97], v[36:37], v[0:1], v[18:19] op_sel_hi:[1,0,1] neg_lo:[0,0,1] neg_hi:[0,0,1]
	v_pk_mul_f32 v[18:19], v[134:135], v[108:109]
	ds_read_b128 v[62:65], v249
	v_pk_fma_f32 v[102:103], v[34:35], v[0:1], v[18:19] op_sel_hi:[1,0,1] neg_lo:[0,0,1] neg_hi:[0,0,1]
	v_pk_mul_f32 v[18:19], v[134:135], v[118:119]
	v_pk_mul_f32 v[212:213], v[20:21], v[20:21]
	v_pk_fma_f32 v[32:33], v[40:41], v[0:1], v[18:19] op_sel_hi:[1,0,1] neg_lo:[0,0,1] neg_hi:[0,0,1]
	v_pk_mul_f32 v[18:19], v[134:135], v[116:117]
	v_pk_mul_f32 v[218:219], v[100:101], v[100:101]
	v_pk_fma_f32 v[104:105], v[38:39], v[0:1], v[18:19] op_sel_hi:[1,0,1] neg_lo:[0,0,1] neg_hi:[0,0,1]
	v_pk_mul_f32 v[18:19], v[134:135], v[122:123]
	v_pk_mul_f32 v[216:217], v[90:91], v[90:91]
	v_pk_fma_f32 v[34:35], v[44:45], v[0:1], v[18:19] op_sel_hi:[1,0,1] neg_lo:[0,0,1] neg_hi:[0,0,1]
	v_pk_mul_f32 v[18:19], v[134:135], v[120:121]
	v_pk_mul_f32 v[44:45], v[134:135], v[200:201]
	v_pk_fma_f32 v[106:107], v[42:43], v[0:1], v[18:19] op_sel_hi:[1,0,1] neg_lo:[0,0,1] neg_hi:[0,0,1]
	v_pk_mul_f32 v[18:19], v[134:135], v[126:127]
	v_pk_fma_f32 v[42:43], v[54:55], v[0:1], v[22:23] op_sel_hi:[1,0,1] neg_lo:[0,0,1] neg_hi:[0,0,1]
	v_pk_fma_f32 v[36:37], v[48:49], v[0:1], v[18:19] op_sel_hi:[1,0,1] neg_lo:[0,0,1] neg_hi:[0,0,1]
	v_pk_mul_f32 v[18:19], v[134:135], v[124:125]
	v_pk_mul_f32 v[22:23], v[134:135], v[202:203]
	v_pk_fma_f32 v[108:109], v[46:47], v[0:1], v[18:19] op_sel_hi:[1,0,1] neg_lo:[0,0,1] neg_hi:[0,0,1]
	v_pk_mul_f32 v[18:19], v[134:135], v[130:131]
	v_pk_fma_f32 v[22:23], v[60:61], v[0:1], v[22:23] op_sel_hi:[1,0,1] neg_lo:[0,0,1] neg_hi:[0,0,1]
	v_pk_fma_f32 v[38:39], v[68:69], v[0:1], v[18:19] op_sel_hi:[1,0,1] neg_lo:[0,0,1] neg_hi:[0,0,1]
	v_pk_mul_f32 v[18:19], v[134:135], v[128:129]
	v_pk_fma_f32 v[44:45], v[58:59], v[0:1], v[44:45] op_sel_hi:[1,0,1] neg_lo:[0,0,1] neg_hi:[0,0,1]
	v_pk_fma_f32 v[46:47], v[66:67], v[0:1], v[18:19] op_sel_hi:[1,0,1] neg_lo:[0,0,1] neg_hi:[0,0,1]
	v_pk_mul_f32 v[18:19], v[134:135], v[150:151]
	v_pk_mul_f32 v[222:223], v[110:111], v[110:111]
; __device__ __forceinline__ unsigned pkbf(float lo, float hi) { f32x2 v = {lo, hi}; bf16x2v b = __builtin_convertvector(v, bf16x2v); return __builtin_bit_cast(unsigned, b); }
; __device__ __forceinline__ void attn_unit(const TI ti, CArgs& a, int b, int hd, int qrow0, int st_lo, int st_hi, float mfix, float lam, float lam_init, const float* subg, unsigned char* ldsg) {
;     ...
;             for (int i = 0; i < 16; ++i) { const float o = O[e][i] * linv - lam * X[(e * 16 + i) * 64 + lane]; O[e][i] = o; ssq += o * o; }
;         ssq += __shfl_xor(ssq, 32);
;         const float sc = rsqrtf(ssq * (1.f / 128.f) + 1e-6f) * (1.f - lam_init);
;         bf16_t* op = Qb + (size_t)(qrow0 + qt * 32 + r) * 1024 + hd * 128;
; #pragma unroll
;         for (int e = 0; e < 4; ++e)
; #pragma unroll
;             for (int g4 = 0; g4 < 4; ++g4) {
;                 const int e0 = e * 32 + 8 * g4 + 4 * h; const f32x4 sg = *(const f32x4*)(subg + e0);
;                 u32x2 o; o.x = pkbf(O[e][4 * g4 + 0] * sc * sg.x, O[e][4 * g4 + 1] * sc * sg.y); o.y = pkbf(O[e][4 * g4 + 2] * sc * sg.z, O[e][4 * g4 + 3] * sc * sg.w);
;                 *(u32x2*)(op + e0) = o;
	v_pk_fma_f32 v[24:25], v[72:73], v[0:1], v[18:19] op_sel_hi:[1,0,1] neg_lo:[0,0,1] neg_hi:[0,0,1]
	v_pk_mul_f32 v[18:19], v[134:135], v[132:133]
	v_pk_mul_f32 v[220:221], v[92:93], v[92:93]
	v_pk_fma_f32 v[48:49], v[70:71], v[0:1], v[18:19] op_sel_hi:[1,0,1] neg_lo:[0,0,1] neg_hi:[0,0,1]
	v_pk_mul_f32 v[18:19], v[134:135], v[182:183]
	v_pk_mul_f32 v[226:227], v[112:113], v[112:113]
	v_pk_fma_f32 v[26:27], v[76:77], v[0:1], v[18:19] op_sel_hi:[1,0,1] neg_lo:[0,0,1] neg_hi:[0,0,1]
	v_pk_mul_f32 v[18:19], v[134:135], v[170:171]
	v_pk_mul_f32 v[224:225], v[94:95], v[94:95]
	v_pk_fma_f32 v[66:67], v[74:75], v[0:1], v[18:19] op_sel_hi:[1,0,1] neg_lo:[0,0,1] neg_hi:[0,0,1]
	v_pk_mul_f32 v[18:19], v[134:135], v[198:199]
	v_pk_mul_f32 v[228:229], v[102:103], v[102:103]
	v_pk_fma_f32 v[28:29], v[80:81], v[0:1], v[18:19] op_sel_hi:[1,0,1] neg_lo:[0,0,1] neg_hi:[0,0,1]
	v_pk_mul_f32 v[18:19], v[134:135], v[184:185]
	v_pk_mul_f32 v[114:115], v[96:97], v[96:97]
	v_pk_fma_f32 v[68:69], v[78:79], v[0:1], v[18:19] op_sel_hi:[1,0,1] neg_lo:[0,0,1] neg_hi:[0,0,1]
	v_pk_mul_f32 v[18:19], v[134:135], v[206:207]
	v_pk_mul_f32 v[116:117], v[104:105], v[104:105]
	v_pk_fma_f32 v[30:31], v[52:53], v[0:1], v[18:19] op_sel_hi:[1,0,1] neg_lo:[0,0,1] neg_hi:[0,0,1]
	v_pk_mul_f32 v[18:19], v[134:135], v[204:205]
	v_pk_mul_f32 v[118:119], v[32:33], v[32:33]
	v_pk_fma_f32 v[40:41], v[50:51], v[0:1], v[18:19] op_sel_hi:[1,0,1] neg_lo:[0,0,1] neg_hi:[0,0,1]
	s_waitcnt lgkmcnt(0)
	v_pk_mul_f32 v[18:19], v[134:135], v[210:211]
	v_pk_mul_f32 v[120:121], v[106:107], v[106:107]
	v_pk_fma_f32 v[18:19], v[56:57], v[0:1], v[18:19] op_sel_hi:[1,0,1] neg_lo:[0,0,1] neg_hi:[0,0,1]
	v_add_f32_e32 v0, v214, v215
	v_add_f32_e32 v0, v0, v212
	v_add_f32_e32 v0, v0, v213
	v_add_f32_e32 v0, v0, v218
	v_add_f32_e32 v0, v0, v219
	v_add_f32_e32 v0, v0, v216
	v_add_f32_e32 v0, v0, v217
	v_add_f32_e32 v0, v0, v222
	v_add_f32_e32 v0, v0, v223
	v_add_f32_e32 v0, v0, v220
	v_add_f32_e32 v0, v0, v221
	v_add_f32_e32 v0, v0, v226
	v_add_f32_e32 v0, v0, v227
	v_add_f32_e32 v0, v0, v224
	v_add_f32_e32 v0, v0, v225
	v_add_f32_e32 v0, v0, v228
	v_add_f32_e32 v0, v0, v229
	v_add_f32_e32 v0, v0, v114
	v_add_f32_e32 v0, v0, v115
	v_add_f32_e32 v0, v0, v116
	v_add_f32_e32 v0, v0, v117
	v_add_f32_e32 v0, v0, v118
	v_add_f32_e32 v0, v0, v119
	v_add_f32_e32 v0, v0, v120
	v_pk_mul_f32 v[122:123], v[34:35], v[34:35]
	v_add_f32_e32 v0, v0, v121
	v_add_f32_e32 v0, v0, v122
	v_pk_mul_f32 v[124:125], v[108:109], v[108:109]
	v_add_f32_e32 v0, v0, v123
	v_add_f32_e32 v0, v0, v124
	v_pk_mul_f32 v[126:127], v[36:37], v[36:37]
	v_add_f32_e32 v0, v0, v125
	v_add_f32_e32 v0, v0, v126
	v_pk_mul_f32 v[128:129], v[46:47], v[46:47]
	v_add_f32_e32 v0, v0, v127
	v_add_f32_e32 v0, v0, v128
	v_pk_mul_f32 v[130:131], v[38:39], v[38:39]
	v_add_f32_e32 v0, v0, v129
	v_add_f32_e32 v0, v0, v130
	v_pk_mul_f32 v[70:71], v[48:49], v[48:49]
	v_add_f32_e32 v0, v0, v131
	v_add_f32_e32 v0, v0, v70
	v_pk_mul_f32 v[72:73], v[24:25], v[24:25]
	v_add_f32_e32 v0, v0, v71
	v_add_f32_e32 v0, v0, v72
	v_pk_mul_f32 v[74:75], v[66:67], v[66:67]
	v_add_f32_e32 v0, v0, v73
	v_add_f32_e32 v0, v0, v74
	v_pk_mul_f32 v[76:77], v[26:27], v[26:27]
	v_add_f32_e32 v0, v0, v75
	v_add_f32_e32 v0, v0, v76
	v_pk_mul_f32 v[78:79], v[68:69], v[68:69]
	v_add_f32_e32 v0, v0, v77
	v_add_f32_e32 v0, v0, v78
	v_pk_mul_f32 v[80:81], v[28:29], v[28:29]
	v_add_f32_e32 v0, v0, v79
	v_add_f32_e32 v0, v0, v80
	v_pk_mul_f32 v[50:51], v[40:41], v[40:41]
	v_add_f32_e32 v0, v0, v81
	v_add_f32_e32 v0, v0, v50
	v_pk_mul_f32 v[52:53], v[30:31], v[30:31]
	v_add_f32_e32 v0, v0, v51
	v_add_f32_e32 v0, v0, v52
	v_pk_mul_f32 v[54:55], v[42:43], v[42:43]
	v_add_f32_e32 v0, v0, v53
	v_add_f32_e32 v0, v0, v54
	v_pk_mul_f32 v[56:57], v[18:19], v[18:19]
	v_add_f32_e32 v0, v0, v55
	v_add_f32_e32 v0, v0, v56
	v_pk_mul_f32 v[58:59], v[44:45], v[44:45]
	v_add_f32_e32 v0, v0, v57
	v_add_f32_e32 v0, v0, v58
	v_pk_mul_f32 v[60:61], v[22:23], v[22:23]
	v_add_f32_e32 v0, v0, v59
	v_add_f32_e32 v0, v0, v60
	v_pk_mul_f32 v[86:87], v[82:83], v[82:83]
	v_add_f32_e32 v0, v0, v61
	v_add_f32_e32 v0, v0, v86
	v_pk_mul_f32 v[98:99], v[84:85], v[84:85]
	v_add_f32_e32 v0, v0, v87
	v_add_f32_e32 v0, v0, v98
	v_add_f32_e32 v0, v0, v99
	ds_bpermute_b32 v50, v137, v0
	s_waitcnt lgkmcnt(0)
	v_add_f32_e32 v0, v0, v50
	v_fmamk_f32 v0, v0, 0x3c000000, v172
	v_mul_f32_e32 v50, 0x4b800000, v0
	v_cmp_gt_f32_e32 vcc, s8, v0
	s_nop 1
	v_cndmask_b32_e32 v0, v0, v50, vcc
	v_rsq_f32_e32 v50, v0
	v_lshlrev_b32_e32 v0, 1, v146
	v_lshl_add_u64 v[54:55], v[152:153], 0, v[0:1]
	v_mul_f32_e32 v0, 0x45800000, v50
	v_cndmask_b32_e32 v0, v50, v0, vcc
	v_mul_f32_e32 v0, v165, v0
	v_pk_mul_f32 v[50:51], v[88:89], v[0:1] op_sel_hi:[1,0]
	v_pk_mul_f32 v[20:21], v[20:21], v[0:1] op_sel_hi:[1,0]
	s_waitcnt lgkmcnt(0)
	v_pk_mul_f32 v[50:51], v[62:63], v[50:51]
	v_pk_mul_f32 v[20:21], v[64:65], v[20:21]
	v_cvt_pk_bf16_f32 v50, v50, v51
	v_cvt_pk_bf16_f32 v51, v20, v21
	global_store_dwordx2 v[54:55], v[50:51], off
	ds_read_b128 v[50:53], v249 offset:32
	v_pk_mul_f32 v[20:21], v[100:101], v[0:1] op_sel_hi:[1,0]
	v_pk_mul_f32 v[56:57], v[92:93], v[0:1] op_sel_hi:[1,0]
	v_pk_mul_f32 v[32:33], v[32:33], v[0:1] op_sel_hi:[1,0]
	v_pk_mul_f32 v[36:37], v[36:37], v[0:1] op_sel_hi:[1,0]
	v_pk_mul_f32 v[24:25], v[24:25], v[0:1] op_sel_hi:[1,0]
	v_pk_mul_f32 v[28:29], v[28:29], v[0:1] op_sel_hi:[1,0]
	v_pk_mul_f32 v[18:19], v[18:19], v[0:1] op_sel_hi:[1,0]
	v_pk_mul_f32 v[22:23], v[22:23], v[0:1] op_sel_hi:[1,0]
	s_waitcnt lgkmcnt(0)
; __device__ __forceinline__ unsigned pkbf(float lo, float hi) { f32x2 v = {lo, hi}; bf16x2v b = __builtin_convertvector(v, bf16x2v); return __builtin_bit_cast(unsigned, b); }
; __device__ __forceinline__ void attn_unit(const TI ti, CArgs& a, int b, int hd, int qrow0, int st_lo, int st_hi, float mfix, float lam, float lam_init, const float* subg, unsigned char* ldsg) {
;     ...
; #pragma unroll
;         for (int e = 0; e < 4; ++e)
; #pragma unroll
;             for (int g4 = 0; g4 < 4; ++g4) {
;                 const int e0 = e * 32 + 8 * g4 + 4 * h; const f32x4 sg = *(const f32x4*)(subg + e0);
;                 u32x2 o; o.x = pkbf(O[e][4 * g4 + 0] * sc * sg.x, O[e][4 * g4 + 1] * sc * sg.y); o.y = pkbf(O[e][4 * g4 + 2] * sc * sg.z, O[e][4 * g4 + 3] * sc * sg.w);
;                 *(u32x2*)(op + e0) = o;
;             }
	v_pk_mul_f32 v[20:21], v[50:51], v[20:21]
	v_pk_mul_f32 v[50:51], v[90:91], v[0:1] op_sel_hi:[1,0]
	v_cvt_pk_bf16_f32 v20, v20, v21
	v_pk_mul_f32 v[50:51], v[52:53], v[50:51]
	s_nop 0
	v_cvt_pk_bf16_f32 v21, v50, v51
	global_store_dwordx2 v[54:55], v[20:21], off offset:16
	ds_read_b128 v[50:53], v249 offset:64
	v_pk_mul_f32 v[20:21], v[110:111], v[0:1] op_sel_hi:[1,0]
	s_waitcnt lgkmcnt(0)
	v_pk_mul_f32 v[20:21], v[50:51], v[20:21]
	v_pk_mul_f32 v[50:51], v[52:53], v[56:57]
	v_cvt_pk_bf16_f32 v20, v20, v21
	v_cvt_pk_bf16_f32 v21, v50, v51
	global_store_dwordx2 v[54:55], v[20:21], off offset:32
	ds_read_b128 v[50:53], v249 offset:96
	v_pk_mul_f32 v[20:21], v[112:113], v[0:1] op_sel_hi:[1,0]
	v_pk_mul_f32 v[56:57], v[94:95], v[0:1] op_sel_hi:[1,0]
	s_waitcnt lgkmcnt(0)
	v_pk_mul_f32 v[20:21], v[50:51], v[20:21]
	v_pk_mul_f32 v[50:51], v[52:53], v[56:57]
	v_cvt_pk_bf16_f32 v20, v20, v21
	v_cvt_pk_bf16_f32 v21, v50, v51
	global_store_dwordx2 v[54:55], v[20:21], off offset:48
	ds_read_b128 v[50:53], v249 offset:128
	v_pk_mul_f32 v[20:21], v[102:103], v[0:1] op_sel_hi:[1,0]
	v_pk_mul_f32 v[56:57], v[96:97], v[0:1] op_sel_hi:[1,0]
	s_waitcnt lgkmcnt(0)
	v_pk_mul_f32 v[20:21], v[50:51], v[20:21]
	v_pk_mul_f32 v[50:51], v[52:53], v[56:57]
	v_cvt_pk_bf16_f32 v20, v20, v21
	v_cvt_pk_bf16_f32 v21, v50, v51
	global_store_dwordx2 v[54:55], v[20:21], off offset:64
	ds_read_b128 v[50:53], v249 offset:160
	v_pk_mul_f32 v[20:21], v[104:105], v[0:1] op_sel_hi:[1,0]
	s_waitcnt lgkmcnt(0)
	v_pk_mul_f32 v[32:33], v[52:53], v[32:33]
	v_pk_mul_f32 v[20:21], v[50:51], v[20:21]
	s_nop 0
	v_cvt_pk_bf16_f32 v20, v20, v21
	v_cvt_pk_bf16_f32 v21, v32, v33
	global_store_dwordx2 v[54:55], v[20:21], off offset:80
	ds_read_b128 v[50:53], v249 offset:192
	v_pk_mul_f32 v[20:21], v[106:107], v[0:1] op_sel_hi:[1,0]
	v_pk_mul_f32 v[32:33], v[34:35], v[0:1] op_sel_hi:[1,0]
	s_waitcnt lgkmcnt(0)
	v_pk_mul_f32 v[20:21], v[50:51], v[20:21]
	v_pk_mul_f32 v[32:33], v[52:53], v[32:33]
	v_cvt_pk_bf16_f32 v20, v20, v21
	v_cvt_pk_bf16_f32 v21, v32, v33
	global_store_dwordx2 v[54:55], v[20:21], off offset:96
	ds_read_b128 v[32:35], v249 offset:224
	v_pk_mul_f32 v[20:21], v[108:109], v[0:1] op_sel_hi:[1,0]
	s_waitcnt lgkmcnt(0)
	v_pk_mul_f32 v[20:21], v[20:21], v[32:33]
	v_pk_mul_f32 v[32:33], v[36:37], v[34:35]
	v_cvt_pk_bf16_f32 v20, v20, v21
	v_cvt_pk_bf16_f32 v21, v32, v33
	global_store_dwordx2 v[54:55], v[20:21], off offset:112
	ds_read_b128 v[32:35], v249 offset:256
	v_pk_mul_f32 v[20:21], v[46:47], v[0:1] op_sel_hi:[1,0]
	v_pk_mul_f32 v[36:37], v[38:39], v[0:1] op_sel_hi:[1,0]
	s_waitcnt lgkmcnt(0)
	v_pk_mul_f32 v[20:21], v[20:21], v[32:33]
	v_pk_mul_f32 v[32:33], v[36:37], v[34:35]
	v_cvt_pk_bf16_f32 v20, v20, v21
	v_cvt_pk_bf16_f32 v21, v32, v33
	global_store_dwordx2 v[54:55], v[20:21], off offset:128
	ds_read_b128 v[32:35], v249 offset:288
	v_pk_mul_f32 v[20:21], v[48:49], v[0:1] op_sel_hi:[1,0]
	s_waitcnt lgkmcnt(0)
	v_pk_mul_f32 v[24:25], v[24:25], v[34:35]
	v_pk_mul_f32 v[20:21], v[20:21], v[32:33]
	s_nop 0
	v_cvt_pk_bf16_f32 v20, v20, v21
	v_cvt_pk_bf16_f32 v21, v24, v25
	global_store_dwordx2 v[54:55], v[20:21], off offset:144
	ds_read_b128 v[32:35], v249 offset:320
	v_pk_mul_f32 v[20:21], v[66:67], v[0:1] op_sel_hi:[1,0]
	v_pk_mul_f32 v[24:25], v[26:27], v[0:1] op_sel_hi:[1,0]
	s_waitcnt lgkmcnt(0)
	v_pk_mul_f32 v[20:21], v[20:21], v[32:33]
	v_pk_mul_f32 v[24:25], v[24:25], v[34:35]
	v_cvt_pk_bf16_f32 v20, v20, v21
	v_cvt_pk_bf16_f32 v21, v24, v25
	global_store_dwordx2 v[54:55], v[20:21], off offset:160
	ds_read_b128 v[24:27], v249 offset:352
	v_pk_mul_f32 v[20:21], v[68:69], v[0:1] op_sel_hi:[1,0]
	s_waitcnt lgkmcnt(0)
	v_pk_mul_f32 v[20:21], v[20:21], v[24:25]
	v_pk_mul_f32 v[24:25], v[28:29], v[26:27]
	v_cvt_pk_bf16_f32 v20, v20, v21
	v_cvt_pk_bf16_f32 v21, v24, v25
	global_store_dwordx2 v[54:55], v[20:21], off offset:176
	ds_read_b128 v[24:27], v249 offset:384
	v_pk_mul_f32 v[20:21], v[40:41], v[0:1] op_sel_hi:[1,0]
	v_pk_mul_f32 v[28:29], v[30:31], v[0:1] op_sel_hi:[1,0]
	s_waitcnt lgkmcnt(0)
	v_pk_mul_f32 v[20:21], v[20:21], v[24:25]
	v_pk_mul_f32 v[24:25], v[28:29], v[26:27]
	v_cvt_pk_bf16_f32 v20, v20, v21
	v_cvt_pk_bf16_f32 v21, v24, v25
	global_store_dwordx2 v[54:55], v[20:21], off offset:192
	ds_read_b128 v[24:27], v249 offset:416
	v_pk_mul_f32 v[20:21], v[42:43], v[0:1] op_sel_hi:[1,0]
	s_waitcnt lgkmcnt(0)
	v_pk_mul_f32 v[18:19], v[18:19], v[26:27]
	v_pk_mul_f32 v[20:21], v[20:21], v[24:25]
	v_pk_mul_f32 v[24:25], v[44:45], v[0:1] op_sel_hi:[1,0]
	v_cvt_pk_bf16_f32 v20, v20, v21
	v_cvt_pk_bf16_f32 v21, v18, v19
	global_store_dwordx2 v[54:55], v[20:21], off offset:208
	ds_read_b128 v[18:21], v249 offset:448
	s_waitcnt lgkmcnt(0)
	v_pk_mul_f32 v[18:19], v[24:25], v[18:19]
	v_pk_mul_f32 v[20:21], v[22:23], v[20:21]
	v_cvt_pk_bf16_f32 v18, v18, v19
	v_cvt_pk_bf16_f32 v19, v20, v21
	global_store_dwordx2 v[54:55], v[18:19], off offset:224
	ds_read_b128 v[18:21], v249 offset:480
	v_pk_mul_f32 v[22:23], v[82:83], v[0:1] op_sel_hi:[1,0]
	v_pk_mul_f32 v[24:25], v[84:85], v[0:1] op_sel_hi:[1,0]
	s_waitcnt lgkmcnt(0)
	v_pk_mul_f32 v[18:19], v[22:23], v[18:19]
	v_pk_mul_f32 v[20:21], v[24:25], v[20:21]
	v_cvt_pk_bf16_f32 v18, v18, v19
	v_cvt_pk_bf16_f32 v19, v20, v21
	global_store_dwordx2 v[54:55], v[18:19], off offset:240
	s_branch .LBB0_331
